# mixB prompt: LN gamma/beta loads hoisted to item top, LN-partial load batches merged; LRU pass-1 conv-weight loads joined with row loads
# speedup vs baseline: 1.0033x; 1.0033x over previous
.LBB0_640:
	s_andn2_b64 vcc, exec, s[18:19]
	s_cbranch_vccnz .LBB0_637
	v_mov_b32_e32 v40, v195
	s_load_dwordx4 s[52:55], s[80:81], 0xa0
	s_and_b32 s23, s1, 0xffffff80
	v_and_b32_e32 v41, 63, v40
	v_ashrrev_i32_e32 v38, 6, v40
	s_and_b32 s20, s22, 3
	v_lshl_or_b32 v2, v41, 1, s23
	v_mov_b64_e32 v[0:1], s[12:13]
	v_mad_i64_i32 v[0:1], s[18:19], v2, s68, v[0:1]
	s_lshl_b32 s96, s20, 9
	v_lshlrev_b32_e32 v32, 5, v38
	v_lshl_add_u64 v[0:1], v[0:1], 0, s[96:97]
	v_ashrrev_i32_e32 v33, 31, v32
	v_lshl_add_u64 v[4:5], v[32:33], 1, v[0:1]
	s_mov_b64 s[18:19], 0x1000
	v_lshl_add_u64 v[6:7], v[4:5], 0, s[18:19]
	s_movk_i32 s18, 0x1000
	v_add_co_u32_e32 v0, vcc, s18, v4
	s_mov_b64 s[18:19], 0x5800
	s_nop 0
	v_addc_co_u32_e32 v1, vcc, 0, v5, vcc
	v_lshl_add_u64 v[24:25], v[4:5], 0, s[18:19]
	v_add_co_u32_e32 v4, vcc, 0x5000, v4
	global_load_dwordx4 v[16:19], v[0:1], off
	s_nop 0
	global_load_dwordx4 v[0:3], v[6:7], off offset:48
	global_load_dwordx4 v[8:11], v[6:7], off offset:32
	global_load_dwordx4 v[20:23], v[6:7], off offset:16
	v_addc_co_u32_e32 v5, vcc, 0, v5, vcc
	global_load_dwordx4 v[28:31], v[4:5], off offset:2048
	s_nop 0
	global_load_dwordx4 v[4:7], v[24:25], off offset:48
	global_load_dwordx4 v[12:15], v[24:25], off offset:32
	s_nop 0
	global_load_dwordx4 v[24:27], v[24:25], off offset:16
	s_lshl_b64 s[56:57], s[6:7], 2
	s_lshl_b32 s58, s20, 10
	v_lshlrev_b32_e32 v76, 2, v32
	s_waitcnt lgkmcnt(0)
	s_add_u32 s52, s52, s56
	s_addc_u32 s53, s53, s57
	s_add_u32 s52, s52, s58
	s_addc_u32 s53, s53, 0
	s_add_u32 s54, s54, s56
	s_addc_u32 s55, s55, s57
	s_add_u32 s54, s54, s58
	s_addc_u32 s55, s55, 0
	global_load_dwordx4 v[78:81], v76, s[52:53]
	global_load_dwordx4 v[82:85], v76, s[54:55]
	global_load_dwordx4 v[86:89], v76, s[54:55] offset:16
	global_load_dwordx4 v[90:93], v76, s[52:53] offset:16
	global_load_dwordx4 v[94:97], v76, s[54:55] offset:32
	global_load_dwordx4 v[98:101], v76, s[52:53] offset:32
	global_load_dwordx4 v[102:105], v76, s[52:53] offset:48
	global_load_dwordx4 v[106:109], v76, s[54:55] offset:48
	global_load_dwordx4 v[110:113], v76, s[54:55] offset:64
	global_load_dwordx4 v[114:117], v76, s[52:53] offset:64
	global_load_dwordx4 v[118:121], v76, s[52:53] offset:80
	global_load_dwordx4 v[122:125], v76, s[54:55] offset:80
	global_load_dwordx4 v[126:129], v76, s[54:55] offset:96
	global_load_dwordx4 v[130:133], v76, s[52:53] offset:96
	global_load_dwordx4 v[134:137], v76, s[52:53] offset:112
	global_load_dwordx4 v[138:141], v76, s[54:55] offset:112
	s_movk_i32 s18, 0x80
	v_cmp_gt_i32_e32 vcc, s18, v40
	s_and_saveexec_b64 s[18:19], vcc
	s_cbranch_execz .LBB0_643
	v_add_u32_e32 v34, s23, v40
	v_ashrrev_i32_e32 v35, 31, v34
	v_lshlrev_b64 v[34:35], 7, v[34:35]
	v_lshl_add_u64 v[54:55], s[14:15], 0, v[34:35]
	global_load_dwordx4 v[34:37], v[54:55], off offset:48
	global_load_dwordx4 v[42:45], v[54:55], off offset:32
	global_load_dwordx4 v[46:49], v[54:55], off offset:16
	global_load_dwordx4 v[50:53], v[54:55], off
	global_load_dwordx4 v[142:145], v[54:55], off offset:112
	global_load_dwordx4 v[146:149], v[54:55], off offset:96
	global_load_dwordx4 v[150:153], v[54:55], off offset:80
	global_load_dwordx4 v[154:157], v[54:55], off offset:64
	s_mov_b32 s24, 0x3a800000
	s_waitcnt vmcnt(7)
	v_add_f32_e32 v34, v34, v36
	s_waitcnt vmcnt(6)
	v_add_f32_e32 v42, v42, v44
	s_waitcnt vmcnt(5)
	v_add_f32_e32 v46, v46, v48
	s_waitcnt vmcnt(4)
	v_add_f32_e32 v39, v50, v52
	v_add_f32_e32 v39, 0, v39
	v_add_f32_e32 v50, v51, v53
	v_add_f32_e32 v50, 0, v50
	v_add_f32_e32 v39, v39, v46
	v_add_f32_e32 v46, v47, v49
	v_add_f32_e32 v46, v50, v46
	v_add_f32_e32 v39, v39, v42
	v_add_f32_e32 v42, v43, v45
	v_add_f32_e32 v42, v46, v42
	v_add_f32_e32 v39, v39, v34
	v_add_f32_e32 v34, v35, v37
	v_add_f32_e32 v56, v42, v34
	s_waitcnt vmcnt(3)
	v_add_f32_e32 v142, v142, v144
	s_waitcnt vmcnt(2)
	v_add_f32_e32 v146, v146, v148
	s_waitcnt vmcnt(1)
	v_add_f32_e32 v150, v150, v152
	s_waitcnt vmcnt(0)
	v_add_f32_e32 v154, v154, v156
	v_add_f32_e32 v39, v39, v154
	v_add_f32_e32 v154, v155, v157
	v_add_f32_e32 v39, v39, v150
	v_add_f32_e32 v154, v56, v154
	v_add_f32_e32 v150, v151, v153
	v_add_f32_e32 v39, v39, v146
	v_add_f32_e32 v150, v154, v150
	v_add_f32_e32 v146, v147, v149
	v_add_f32_e32 v142, v39, v142
	v_add_f32_e32 v146, v150, v146
	v_add_f32_e32 v143, v143, v145
	v_mul_f32_e32 v142, 0x3a800000, v142
	v_add_f32_e32 v143, v146, v143
	v_mul_f32_e32 v144, v142, v142
	v_fma_f32 v143, v143, s24, -v144
	v_max_f32_e32 v143, 0, v143
	v_add_f32_e32 v143, 0x358637bd, v143
	v_rsq_f32_e32 v143, v143
	v_lshl_add_u32 v144, v40, 3, 0
	ds_write_b64 v144, v[142:143]
.LBB0_643:
	s_or_b64 exec, exec, s[18:19]
	s_load_dwordx4 s[28:31], s[80:81], 0xa0
	s_load_dwordx2 s[18:19], s[80:81], 0xb8
	s_lshl_b32 s24, s20, 8
	s_lshl_b64 s[26:27], s[6:7], 2
	v_lshlrev_b64 v[36:37], 2, v[32:33]
	s_waitcnt lgkmcnt(0)
	s_add_u32 s21, s30, s26
	s_addc_u32 s25, s31, s27
	s_lshl_b32 s34, s24, 2
	s_add_u32 s30, s21, s34
	s_addc_u32 s31, s25, 0
	s_add_u32 s21, s28, s26
	s_addc_u32 s25, s29, s27
	s_add_u32 s26, s21, s34
	s_addc_u32 s27, s25, 0
	v_lshl_add_u64 v[34:35], s[26:27], 0, v[36:37]
	s_barrier
	s_waitcnt vmcnt(0)
	v_mov_b64_e32 v[42:43], v[78:79]
	v_mov_b64_e32 v[44:45], v[80:81]
	v_lshl_add_u64 v[36:37], s[30:31], 0, v[36:37]
	v_mov_b64_e32 v[46:47], v[82:83]
	v_mov_b64_e32 v[48:49], v[84:85]
	v_mov_b64_e32 v[50:51], v[86:87]
	v_mov_b64_e32 v[52:53], v[88:89]
	v_mov_b64_e32 v[54:55], v[90:91]
	v_mov_b64_e32 v[56:57], v[92:93]
	v_lshl_add_u32 v33, v41, 4, 0
	s_waitcnt vmcnt(0)
	v_lshlrev_b32_e32 v39, 16, v16
	v_and_b32_e32 v58, 0xffff0000, v16
	v_lshlrev_b32_e32 v59, 16, v17
	v_and_b32_e32 v60, 0xffff0000, v17
	v_lshlrev_b32_e32 v61, 16, v18
	v_and_b32_e32 v62, 0xffff0000, v18
	v_lshlrev_b32_e32 v63, 16, v19
	v_and_b32_e32 v64, 0xffff0000, v19
	ds_read_b128 v[16:19], v33
	s_waitcnt vmcnt(7)
	v_lshlrev_b32_e32 v69, 16, v30
	v_and_b32_e32 v70, 0xffff0000, v30
	v_lshlrev_b32_e32 v71, 16, v31
	v_and_b32_e32 v31, 0xffff0000, v31
	v_mad_i32_i24 v30, v41, -12, v33
	s_movk_i32 s21, 0x2200
	v_lshlrev_b32_e32 v65, 16, v28
	v_and_b32_e32 v66, 0xffff0000, v28
	v_lshlrev_b32_e32 v67, 16, v29
	v_and_b32_e32 v68, 0xffff0000, v29
	v_mad_u64_u32 v[28:29], s[26:27], v38, s21, v[30:31]
	s_waitcnt lgkmcnt(0)
	v_sub_f32_e32 v29, v39, v16
	v_sub_f32_e32 v33, v65, v18
	v_mul_f32_e32 v29, v17, v29
	v_sub_f32_e32 v38, v58, v16
	v_sub_f32_e32 v39, v66, v18
	v_mul_f32_e32 v33, v19, v33
	v_sub_f32_e32 v58, v59, v16
	v_sub_f32_e32 v59, v67, v18
	v_mul_f32_e32 v38, v17, v38
	v_mul_f32_e32 v39, v19, v39
	v_sub_f32_e32 v60, v60, v16
	v_sub_f32_e32 v65, v68, v18
	v_mul_f32_e32 v58, v17, v58
	v_mul_f32_e32 v59, v19, v59
	v_sub_f32_e32 v61, v61, v16
	v_sub_f32_e32 v66, v69, v18
	v_mul_f32_e32 v60, v17, v60
	v_mul_f32_e32 v65, v19, v65
	v_sub_f32_e32 v62, v62, v16
	v_sub_f32_e32 v67, v70, v18
	v_mul_f32_e32 v61, v17, v61
	v_mul_f32_e32 v66, v19, v66
	v_sub_f32_e32 v63, v63, v16
	v_sub_f32_e32 v68, v71, v18
	v_mul_f32_e32 v62, v17, v62
	v_mul_f32_e32 v67, v19, v67
	v_mul_f32_e32 v63, v17, v63
	v_mul_f32_e32 v68, v19, v68
	v_sub_f32_e32 v64, v64, v16
	v_mul_f32_e32 v64, v17, v64
	v_and_b32_e32 v168, 15, v40
	v_and_b32_e32 v184, 48, v41
	s_waitcnt vmcnt(2)
	v_fma_f32 v29, v42, v29, v46
	v_fma_f32 v33, v42, v33, v46
	v_cvt_pk_bf16_f32 v29, v29, v33
	v_fma_f32 v38, v43, v38, v47
	v_fma_f32 v39, v43, v39, v47
	ds_write_b32 v28, v29 offset:1024
	v_cvt_pk_bf16_f32 v29, v38, v39
	v_fma_f32 v42, v44, v58, v48
	v_fma_f32 v43, v44, v59, v48
	ds_write_b32 v28, v29 offset:1296
	v_cvt_pk_bf16_f32 v29, v42, v43
	v_fma_f32 v44, v45, v60, v49
	v_fmac_f32_e32 v49, v45, v65
	ds_write_b32 v28, v29 offset:1568
	v_cvt_pk_bf16_f32 v29, v44, v49
	s_waitcnt vmcnt(0)
	v_fma_f32 v45, v61, v54, v50
	v_fma_f32 v46, v66, v54, v50
	ds_write_b32 v28, v29 offset:1840
	v_cvt_pk_bf16_f32 v29, v45, v46
	v_fma_f32 v47, v62, v55, v51
	v_fma_f32 v48, v67, v55, v51
	ds_write_b32 v28, v29 offset:2112
	v_cvt_pk_bf16_f32 v29, v47, v48
	v_fma_f32 v50, v63, v56, v52
	v_fma_f32 v51, v68, v56, v52
	ds_write_b32 v28, v29 offset:2384
	v_cvt_pk_bf16_f32 v29, v50, v51
	ds_write_b32 v28, v29 offset:2656
	v_sub_f32_e32 v29, v31, v18
	v_mul_f32_e32 v29, v19, v29
	v_fma_f32 v52, v64, v57, v53
	v_fmac_f32_e32 v53, v29, v57
	v_cvt_pk_bf16_f32 v29, v52, v53
	v_mov_b64_e32 v[42:43], v[94:95]
	v_mov_b64_e32 v[44:45], v[96:97]
	v_mov_b64_e32 v[46:47], v[98:99]
	v_mov_b64_e32 v[48:49], v[100:101]
	v_mov_b64_e32 v[50:51], v[102:103]
	v_mov_b64_e32 v[52:53], v[104:105]
	v_mov_b64_e32 v[54:55], v[106:107]
	v_mov_b64_e32 v[56:57], v[108:109]
	v_or_b32_e32 v31, 8, v32
	v_lshlrev_b32_e32 v32, 16, v20
	v_and_b32_e32 v33, 0xffff0000, v20
	v_lshlrev_b32_e32 v38, 16, v21
	v_and_b32_e32 v39, 0xffff0000, v21
	v_mad_u64_u32 v[20:21], s[26:27], v31, s85, v[30:31]
	v_lshlrev_b32_e32 v60, 16, v24
	v_sub_f32_e32 v21, v32, v16
	v_and_b32_e32 v24, 0xffff0000, v24
	v_sub_f32_e32 v30, v60, v18
	v_mul_f32_e32 v21, v17, v21
	v_lshlrev_b32_e32 v61, 16, v25
	v_sub_f32_e32 v31, v33, v16
	v_sub_f32_e32 v24, v24, v18
	v_mul_f32_e32 v30, v19, v30
	v_and_b32_e32 v25, 0xffff0000, v25
	v_sub_f32_e32 v32, v38, v16
	v_sub_f32_e32 v33, v61, v18
	v_mul_f32_e32 v31, v17, v31
	v_mul_f32_e32 v24, v19, v24
	ds_write_b32 v28, v29 offset:2928
	v_lshlrev_b32_e32 v58, 16, v22
	v_lshlrev_b32_e32 v62, 16, v26
	v_sub_f32_e32 v38, v39, v16
	v_sub_f32_e32 v25, v25, v18
	v_mul_f32_e32 v32, v17, v32
	v_mul_f32_e32 v33, v19, v33
	v_and_b32_e32 v22, 0xffff0000, v22
	v_and_b32_e32 v26, 0xffff0000, v26
	v_sub_f32_e32 v39, v58, v16
	v_sub_f32_e32 v58, v62, v18
	v_mul_f32_e32 v38, v17, v38
	v_mul_f32_e32 v25, v19, v25
	v_lshlrev_b32_e32 v59, 16, v23
	v_lshlrev_b32_e32 v63, 16, v27
	v_sub_f32_e32 v22, v22, v16
	v_sub_f32_e32 v26, v26, v18
	v_mul_f32_e32 v39, v17, v39
	v_mul_f32_e32 v58, v19, v58
	v_and_b32_e32 v23, 0xffff0000, v23
	v_sub_f32_e32 v59, v59, v16
	v_sub_f32_e32 v60, v63, v18
	v_mul_f32_e32 v22, v17, v22
	v_mul_f32_e32 v26, v19, v26
	v_and_b32_e32 v27, 0xffff0000, v27
	v_sub_f32_e32 v23, v23, v16
	v_mul_f32_e32 v59, v17, v59
	v_mul_f32_e32 v60, v19, v60
	v_sub_f32_e32 v27, v27, v18
	v_mul_f32_e32 v23, v17, v23
	s_waitcnt vmcnt(2)
	v_fma_f32 v21, v21, v46, v42
	v_fma_f32 v29, v30, v46, v42
	v_cvt_pk_bf16_f32 v21, v21, v29
	v_fma_f32 v30, v31, v47, v43
	v_fma_f32 v24, v24, v47, v43
	ds_write_b32 v20, v21 offset:1024
	v_cvt_pk_bf16_f32 v21, v30, v24
	v_fma_f32 v31, v32, v48, v44
	v_fma_f32 v32, v33, v48, v44
	ds_write_b32 v28, v21 offset:3472
	v_cvt_pk_bf16_f32 v21, v31, v32
	v_fma_f32 v33, v38, v49, v45
	v_fmac_f32_e32 v45, v25, v49
	ds_write_b32 v28, v21 offset:3744
	v_cvt_pk_bf16_f32 v21, v33, v45
	s_waitcnt vmcnt(0)
	v_fma_f32 v25, v39, v50, v54
	v_fma_f32 v38, v58, v50, v54
	ds_write_b32 v28, v21 offset:4016
	v_cvt_pk_bf16_f32 v21, v25, v38
	v_fma_f32 v22, v22, v51, v55
	v_fma_f32 v26, v26, v51, v55
	ds_write_b32 v28, v21 offset:4288
	v_cvt_pk_bf16_f32 v21, v22, v26
	v_fma_f32 v39, v59, v52, v56
	v_fma_f32 v42, v60, v52, v56
	ds_write_b32 v28, v21 offset:4560
	v_cvt_pk_bf16_f32 v21, v39, v42
	v_fma_f32 v23, v23, v53, v57
	ds_write_b32 v28, v21 offset:4832
	v_mul_f32_e32 v21, v19, v27
	v_fmac_f32_e32 v57, v21, v53
	v_cvt_pk_bf16_f32 v21, v23, v57
	v_mov_b64_e32 v[22:23], v[110:111]
	v_mov_b64_e32 v[24:25], v[112:113]
	v_mov_b64_e32 v[30:31], v[114:115]
	v_mov_b64_e32 v[32:33], v[116:117]
	v_mov_b64_e32 v[42:43], v[118:119]
	v_mov_b64_e32 v[44:45], v[120:121]
	v_mov_b64_e32 v[46:47], v[122:123]
	v_mov_b64_e32 v[48:49], v[124:125]
	v_lshlrev_b32_e32 v26, 16, v8
	v_and_b32_e32 v8, 0xffff0000, v8
	v_lshlrev_b32_e32 v38, 16, v11
	v_and_b32_e32 v11, 0xffff0000, v11
	v_lshlrev_b32_e32 v39, 16, v12
	v_and_b32_e32 v12, 0xffff0000, v12
	v_lshlrev_b32_e32 v52, 16, v15
	v_and_b32_e32 v15, 0xffff0000, v15
	v_sub_f32_e32 v8, v8, v16
	v_lshlrev_b32_e32 v27, 16, v9
	v_lshlrev_b32_e32 v50, 16, v13
	v_sub_f32_e32 v26, v26, v16
	v_sub_f32_e32 v39, v39, v18
	v_sub_f32_e32 v12, v12, v18
	v_sub_f32_e32 v11, v11, v16
	v_sub_f32_e32 v15, v15, v18
	v_mul_f32_e32 v8, v17, v8
	v_and_b32_e32 v9, 0xffff0000, v9
	v_and_b32_e32 v13, 0xffff0000, v13
	v_sub_f32_e32 v27, v27, v16
	v_sub_f32_e32 v50, v50, v18
	v_mul_f32_e32 v26, v17, v26
	v_mul_f32_e32 v39, v19, v39
	v_mul_f32_e32 v12, v19, v12
	v_mul_f32_e32 v11, v17, v11
	v_mul_f32_e32 v15, v19, v15
	v_lshlrev_b32_e32 v29, 16, v10
	v_lshlrev_b32_e32 v51, 16, v14
	v_sub_f32_e32 v9, v9, v16
	v_sub_f32_e32 v13, v13, v18
	v_mul_f32_e32 v27, v17, v27
	v_mul_f32_e32 v50, v19, v50
	ds_write_b32 v28, v21 offset:5104
	v_and_b32_e32 v10, 0xffff0000, v10
	v_and_b32_e32 v14, 0xffff0000, v14
	v_sub_f32_e32 v29, v29, v16
	v_sub_f32_e32 v51, v51, v18
	v_mul_f32_e32 v9, v17, v9
	v_mul_f32_e32 v13, v19, v13
	v_sub_f32_e32 v10, v10, v16
	v_sub_f32_e32 v14, v14, v18
	v_mul_f32_e32 v29, v17, v29
	v_mul_f32_e32 v51, v19, v51
	v_sub_f32_e32 v38, v38, v16
	v_sub_f32_e32 v52, v52, v18
	v_mul_f32_e32 v10, v17, v10
	v_mul_f32_e32 v14, v19, v14
	v_mul_f32_e32 v38, v17, v38
	v_mul_f32_e32 v52, v19, v52
	s_waitcnt vmcnt(2)
	v_fma_f32 v8, v8, v31, v23
	v_fma_f32 v21, v26, v30, v22
	v_fma_f32 v22, v39, v30, v22
	v_fma_f32 v12, v12, v31, v23
	s_waitcnt vmcnt(0)
	v_fma_f32 v11, v11, v45, v49
	v_fmac_f32_e32 v49, v15, v45
	v_cvt_pk_bf16_f32 v15, v21, v22
	ds_write_b32 v20, v15 offset:3200
	v_cvt_pk_bf16_f32 v8, v8, v12
	v_fma_f32 v23, v27, v32, v24
	v_fma_f32 v24, v50, v32, v24
	ds_write_b32 v28, v8 offset:5648
	v_cvt_pk_bf16_f32 v8, v23, v24
	v_fma_f32 v9, v9, v33, v25
	v_fmac_f32_e32 v25, v13, v33
	ds_write_b32 v28, v8 offset:5920
	v_cvt_pk_bf16_f32 v8, v9, v25
	v_fma_f32 v13, v29, v42, v46
	v_fma_f32 v26, v51, v42, v46
	ds_write_b32 v28, v8 offset:6192
	v_cvt_pk_bf16_f32 v8, v13, v26
	v_fma_f32 v10, v10, v43, v47
	v_fma_f32 v14, v14, v43, v47
	ds_write_b32 v28, v8 offset:6464
	v_cvt_pk_bf16_f32 v8, v10, v14
	v_fma_f32 v27, v38, v44, v48
	v_fma_f32 v29, v52, v44, v48
	ds_write_b32 v28, v8 offset:6736
	v_cvt_pk_bf16_f32 v8, v27, v29
	ds_write_b32 v28, v8 offset:7008
	v_cvt_pk_bf16_f32 v21, v11, v49
	v_mov_b64_e32 v[8:9], v[126:127]
	v_mov_b64_e32 v[10:11], v[128:129]
	v_mov_b64_e32 v[12:13], v[130:131]
	v_mov_b64_e32 v[14:15], v[132:133]
	v_mov_b64_e32 v[22:23], v[134:135]
	v_mov_b64_e32 v[24:25], v[136:137]
	s_nop 0
	v_mov_b64_e32 v[32:33], v[138:139]
	v_mov_b64_e32 v[34:35], v[140:141]
	v_lshlrev_b32_e32 v26, 16, v0
	v_and_b32_e32 v0, 0xffff0000, v0
	v_lshlrev_b32_e32 v31, 16, v3
	v_and_b32_e32 v3, 0xffff0000, v3
	v_lshlrev_b32_e32 v36, 16, v4
	v_and_b32_e32 v4, 0xffff0000, v4
	v_lshlrev_b32_e32 v39, 16, v7
	v_and_b32_e32 v7, 0xffff0000, v7
	v_sub_f32_e32 v0, v0, v16
	v_lshlrev_b32_e32 v27, 16, v1
	v_and_b32_e32 v1, 0xffff0000, v1
	v_lshlrev_b32_e32 v29, 16, v2
	v_and_b32_e32 v2, 0xffff0000, v2
	v_lshlrev_b32_e32 v37, 16, v5
	v_and_b32_e32 v5, 0xffff0000, v5
	v_lshlrev_b32_e32 v38, 16, v6
	v_and_b32_e32 v6, 0xffff0000, v6
	v_sub_f32_e32 v26, v26, v16
	v_sub_f32_e32 v36, v36, v18
	v_sub_f32_e32 v4, v4, v18
	v_sub_f32_e32 v3, v3, v16
	v_sub_f32_e32 v7, v7, v18
	v_mul_f32_e32 v0, v17, v0
	v_sub_f32_e32 v27, v27, v16
	v_sub_f32_e32 v37, v37, v18
	v_sub_f32_e32 v1, v1, v16
	v_sub_f32_e32 v5, v5, v18
	v_sub_f32_e32 v29, v29, v16
	v_sub_f32_e32 v38, v38, v18
	v_sub_f32_e32 v2, v2, v16
	v_sub_f32_e32 v6, v6, v18
	v_sub_f32_e32 v31, v31, v16
	v_sub_f32_e32 v39, v39, v18
	v_mul_f32_e32 v16, v17, v26
	v_mul_f32_e32 v18, v19, v36
	v_mul_f32_e32 v4, v19, v4
	v_mul_f32_e32 v3, v17, v3
	v_mul_f32_e32 v7, v19, v7
	v_mul_f32_e32 v26, v17, v27
	v_mul_f32_e32 v27, v19, v37
	ds_write_b32 v28, v21 offset:7280
	v_mul_f32_e32 v1, v17, v1
	v_mul_f32_e32 v5, v19, v5
	v_mul_f32_e32 v29, v17, v29
	v_mul_f32_e32 v36, v19, v38
	v_mul_f32_e32 v2, v17, v2
	v_mul_f32_e32 v6, v19, v6
	v_ashrrev_i32_e32 v30, 7, v40
	v_mul_f32_e32 v31, v17, v31
	v_mul_f32_e32 v37, v19, v39
	v_lshl_add_u32 v158, s20, 2, v30
	v_ashrrev_i32_e32 v159, 31, v158
	s_waitcnt vmcnt(2)
	v_fma_f32 v0, v0, v13, v9
	v_fma_f32 v16, v16, v12, v8
	v_fma_f32 v8, v18, v12, v8
	v_fma_f32 v4, v4, v13, v9
	s_waitcnt vmcnt(0)
	v_fma_f32 v3, v3, v25, v35
	v_fmac_f32_e32 v35, v7, v25
	v_cvt_pk_bf16_f32 v7, v16, v8
	ds_write_b32 v20, v7 offset:5376
	v_cvt_pk_bf16_f32 v0, v0, v4
	v_fma_f32 v9, v26, v14, v10
	v_fma_f32 v10, v27, v14, v10
	ds_write_b32 v28, v0 offset:7824
	v_cvt_pk_bf16_f32 v0, v9, v10
	v_fma_f32 v1, v1, v15, v11
	v_fmac_f32_e32 v11, v5, v15
	ds_write_b32 v28, v0 offset:8096
	v_cvt_pk_bf16_f32 v0, v1, v11
	v_fma_f32 v5, v29, v22, v32
	v_fma_f32 v12, v36, v22, v32
	ds_write_b32 v28, v0 offset:8368
	v_cvt_pk_bf16_f32 v0, v5, v12
	v_fma_f32 v2, v2, v23, v33
	v_fma_f32 v6, v6, v23, v33
	ds_write_b32 v28, v0 offset:8640
	v_cvt_pk_bf16_f32 v0, v2, v6
	v_fma_f32 v13, v31, v24, v34
	v_fma_f32 v14, v37, v24, v34
	ds_write_b32 v28, v0 offset:8912
	v_cvt_pk_bf16_f32 v0, v13, v14
	ds_write_b32 v28, v0 offset:9184
	v_cvt_pk_bf16_f32 v0, v3, v35
	ds_write_b32 v28, v0 offset:9456
	v_and_b32_e32 v31, 64, v40
	v_lshlrev_b64 v[0:1], 7, v[158:159]
	v_or3_b32 v0, v0, v31, v168
	v_lshl_add_u64 v[2:3], s[16:17], 0, v[184:185]
	v_lshlrev_b64 v[0:1], 8, v[0:1]
	v_lshl_add_u64 v[28:29], v[2:3], 0, v[0:1]
	v_add_co_u32_e32 v0, vcc, 0x1000, v28
	s_waitcnt lgkmcnt(0)
	s_nop 0
	v_addc_co_u32_e32 v1, vcc, 0, v29, vcc
	s_barrier
	global_load_dwordx4 v[24:27], v[28:29], off
	global_load_dwordx4 v[16:19], v[0:1], off
	v_add_co_u32_e32 v0, vcc, 0x2000, v28
	v_cmp_ne_u32_e64 s[72:73], 0, v31
	s_nop 0
	v_addc_co_u32_e32 v1, vcc, 0, v29, vcc
	v_add_co_u32_e32 v2, vcc, 0x3000, v28
	s_nop 1
	v_addc_co_u32_e32 v3, vcc, 0, v29, vcc
	global_load_dwordx4 v[36:39], v[0:1], off
	global_load_dwordx4 v[20:23], v[2:3], off
	s_and_saveexec_b64 s[20:21], s[72:73]
	s_cbranch_execz .LBB0_645
	global_load_dwordx4 v[8:11], v[28:29], off offset:64

.LBB0_669:
	v_mov_b32_e32 v162, v195
	s_movk_i32 s3, 0x1000
	v_ashrrev_i32_e32 v64, 7, v162
	v_add_u32_e32 v0, s53, v64
	v_ashrrev_i32_e32 v1, 31, v0
	v_bfe_u32 v177, v162, 4, 2
	v_lshlrev_b64 v[0:1], 14, v[0:1]
	v_and_b32_e32 v163, 15, v162
	v_lshl_add_u64 v[0:1], s[8:9], 0, v[0:1]
	v_lshlrev_b32_e32 v184, 4, v177
	v_lshl_add_u64 v[0:1], v[0:1], 0, v[184:185]
	v_lshlrev_b32_e32 v184, 7, v163
	v_lshl_add_u64 v[32:33], v[0:1], 0, v[184:185]
	v_add_co_u32_e32 v34, vcc, s3, v32
	global_load_dwordx4 v[16:19], v[32:33], off
	global_load_dwordx4 v[8:11], v[32:33], off offset:64
	global_load_dwordx4 v[4:7], v[32:33], off offset:2048
	global_load_dwordx4 v[0:3], v[32:33], off offset:2112
	v_addc_co_u32_e32 v35, vcc, 0, v33, vcc
	v_add_co_u32_e32 v12, vcc, s33, v32
	v_lshlrev_b32_e32 v164, 6, v64
	s_nop 0
	v_addc_co_u32_e32 v13, vcc, 0, v33, vcc
	v_add_co_u32_e32 v32, vcc, s50, v32
	global_load_dwordx4 v[56:59], v[34:35], off offset:64
	global_load_dwordx4 v[48:51], v[34:35], off offset:2048
	global_load_dwordx4 v[24:27], v[12:13], off offset:-4096
	global_load_dwordx4 v[40:43], v[12:13], off
	global_load_dwordx4 v[28:31], v[12:13], off offset:64
	global_load_dwordx4 v[20:23], v[12:13], off offset:2048
	s_nop 0
	global_load_dwordx4 v[12:15], v[12:13], off offset:2112
	v_addc_co_u32_e32 v33, vcc, 0, v33, vcc
	global_load_dwordx4 v[60:63], v[34:35], off offset:2112
	global_load_dwordx4 v[52:55], v[32:33], off
	global_load_dwordx4 v[44:47], v[32:33], off offset:64
	global_load_dwordx4 v[36:39], v[32:33], off offset:2048
	s_nop 0
	global_load_dwordx4 v[32:35], v[32:33], off offset:2112
	s_load_dwordx4 s[60:63], s[80:81], 0x68
	s_load_dwordx2 s[18:19], s[80:81], 0x80
	s_load_dwordx4 s[12:15], s[80:81], 0x90
	v_or_b32_e32 v64, s52, v163
	v_add_u32_e32 v64, v64, v164
	v_ashrrev_i32_e32 v65, 31, v64
	v_lshlrev_b64 v[64:65], 2, v[64:65]
	s_waitcnt lgkmcnt(0)
	v_lshl_add_u64 v[66:67], s[14:15], 0, v[64:65]
	v_lshl_add_u64 v[68:69], s[18:19], 0, v[64:65]
	v_lshl_add_u64 v[64:65], s[12:13], 0, v[64:65]
	global_load_dword v176, v[66:67], off
	global_load_dword v171, v[66:67], off offset:64
	global_load_dword v168, v[66:67], off offset:128
	global_load_dword v166, v[66:67], off offset:192
	global_load_dword v174, v[68:69], off
	global_load_dword v172, v[68:69], off offset:64
	global_load_dword v169, v[68:69], off offset:128
	global_load_dword v165, v[68:69], off offset:192
	global_load_dword v175, v[64:65], off
	global_load_dword v173, v[64:65], off offset:64
	global_load_dword v170, v[64:65], off offset:128
	global_load_dword v167, v[64:65], off offset:192
	s_lshl_b32 s3, s16, 8
	v_lshlrev_b32_e32 v64, 3, v162
	s_add_i32 s3, s3, s2
	v_and_b32_e32 v67, 0xf8, v64
	s_ashr_i32 s3, s3, 7
	v_ashrrev_i32_e32 v178, 5, v162
	v_or_b32_e32 v88, s84, v67
	s_lshl_b32 s12, s3, 11
	v_lshlrev_b32_e32 v184, 1, v88
	v_cmp_lt_i32_e32 vcc, 0, v178
	s_or_b32 s17, s12, s89
	v_lshlrev_b32_e32 v66, 2, v178
	v_lshl_add_u64 v[64:65], s[6:7], 0, v[184:185]
	v_mov_b32_e32 v80, 0
	s_or_b64 s[12:13], s[36:37], vcc
	v_mov_b32_e32 v84, 0
	v_mov_b32_e32 v85, 0
	v_mov_b32_e32 v86, 0
	v_mov_b32_e32 v87, 0
	s_and_saveexec_b64 s[14:15], s[12:13]
	s_cbranch_execz .LBB0_671
	v_add3_u32 v68, s17, -3, v66
	v_mad_i64_i32 v[68:69], s[18:19], v68, s68, v[64:65]
	global_load_dwordx4 v[84:87], v[68:69], off

.LBB0_683:
	s_or_b64 exec, exec, s[14:15]
	s_lshl_b32 s12, s16, 16
	s_mov_b64 s[16:17], s[60:61]
	s_mov_b64 s[18:19], s[62:63]
	s_add_i32 s14, s12, 0
	v_lshlrev_b32_e32 v184, 2, v88
	s_add_u32 s12, s16, s76
	s_addc_u32 s13, s17, s77
	v_lshl_add_u64 v[112:113], s[12:13], 0, v[184:185]
	global_load_dwordx4 v[88:91], v184, s[12:13] offset:16
	global_load_dwordx4 v[104:107], v184, s[12:13]
	s_mov_b64 s[12:13], 0x1000
	v_add_co_u32_e32 v98, vcc, s33, v112
	v_lshl_add_u64 v[96:97], v[112:113], 0, s[12:13]
	s_nop 0
	v_addc_co_u32_e32 v99, vcc, 0, v113, vcc
	s_mov_b64 s[12:13], 0x2000
	global_load_dwordx4 v[128:131], v[98:99], off offset:-4096
	global_load_dwordx4 v[120:123], v[96:97], off offset:16
	v_lshl_add_u64 v[96:97], v[112:113], 0, s[12:13]
	s_mov_b64 s[12:13], 0x3000
	v_lshl_add_u64 v[114:115], v[112:113], 0, s[12:13]
	v_add_co_u32_e32 v112, vcc, s50, v112
	s_add_u32 s16, s18, s74
	s_nop 0
	v_addc_co_u32_e32 v113, vcc, 0, v113, vcc
	s_addc_u32 s17, s19, s75
	global_load_dwordx4 v[108:111], v[98:99], off
	s_nop 0
	global_load_dwordx4 v[96:99], v[96:97], off offset:16
	s_nop 0
	global_load_dwordx4 v[132:135], v[112:113], off
	global_load_dwordx4 v[124:127], v[114:115], off offset:16
	s_nop 0
	global_load_dwordx4 v[112:115], v184, s[16:17] offset:16
	global_load_dwordx4 v[116:119], v184, s[16:17]
	s_waitcnt vmcnt(0)
	v_lshlrev_b32_e32 v151, 16, v84
	v_lshlrev_b32_e32 v150, 16, v80
	v_lshlrev_b32_e32 v65, 1, v67
	v_lshlrev_b32_e32 v149, 16, v100
	v_lshlrev_b32_e32 v148, 16, v92
	v_and_b32_e32 v155, 0xffff0000, v84
	v_and_b32_e32 v154, 0xffff0000, v80
	v_and_b32_e32 v138, 0xffff0000, v70
	v_lshlrev_b32_e32 v64, 16, v70
	v_and_b32_e32 v140, 0xffff0000, v69
	v_lshlrev_b32_e32 v70, 16, v69
	v_lshlrev_b32_e32 v158, 16, v81
	v_lshlrev_b32_e32 v159, 16, v85
	v_and_b32_e32 v136, 0xffff0000, v71
	v_lshlrev_b32_e32 v66, 16, v71
	v_lshlrev_b32_e32 v156, 16, v93
	v_lshlrev_b32_e32 v157, 16, v101
	v_and_b32_e32 v84, 0xffff0000, v93
	v_and_b32_e32 v187, 0xffff0000, v102
	v_and_b32_e32 v186, 0xffff0000, v94
	v_lshlrev_b32_e32 v188, 16, v83
	v_lshlrev_b32_e32 v189, 16, v87
	v_lshlrev_b32_e32 v190, 16, v95
	v_lshlrev_b32_e32 v191, 16, v103
	v_and_b32_e32 v87, 0xffff0000, v87
	v_and_b32_e32 v103, 0xffff0000, v103
	s_movk_i32 s12, 0x840
	v_and_b32_e32 v142, 0xffff0000, v68
	v_lshlrev_b32_e32 v68, 16, v68
	v_cmp_eq_u32_e32 vcc, 15, v178
	s_and_b64 s[16:17], s[38:39], vcc
	s_waitcnt vmcnt(9)
	v_mov_b32_e32 v93, v88
	s_waitcnt vmcnt(8)
	v_mov_b32_e32 v145, v104
	s_waitcnt vmcnt(7)
	v_mov_b32_e32 v144, v128
	v_pk_mul_f32 v[146:147], v[144:145], v[150:151]
	v_mov_b32_e32 v104, v129
	v_pk_mul_f32 v[128:129], v[104:105], v[154:155]
	s_waitcnt vmcnt(6)
	v_mov_b32_e32 v88, v121
	s_waitcnt vmcnt(0)
	v_add_f32_e32 v67, v147, v116
	v_add_f32_e32 v67, v146, v67
	v_mov_b32_e32 v146, v132
	v_mov_b32_e32 v147, v108
	v_pk_mul_f32 v[152:153], v[146:147], v[148:149]
	v_add_f32_e32 v69, v129, v117
	v_add_f32_e32 v67, v153, v67
	v_add_f32_e32 v67, v152, v67
	v_and_b32_e32 v153, 0xffff0000, v100
	v_and_b32_e32 v152, 0xffff0000, v92
	v_mov_b32_e32 v108, v133
	v_add_f32_e32 v69, v128, v69
	v_pk_mul_f32 v[128:129], v[108:109], v[152:153]
	s_nop 0
	v_add_f32_e32 v69, v129, v69
	v_add_f32_e32 v69, v128, v69
	v_mov_b32_e32 v128, v130
	v_mov_b32_e32 v129, v106
	v_pk_mul_f32 v[132:133], v[128:129], v[158:159]
	v_mov_b32_e32 v106, v131
	v_add_f32_e32 v71, v133, v118
	v_add_f32_e32 v71, v132, v71
	v_mov_b32_e32 v132, v134
	v_mov_b32_e32 v133, v110
	v_pk_mul_f32 v[160:161], v[132:133], v[156:157]
	v_mov_b32_e32 v110, v135
	v_add_f32_e32 v71, v161, v71
	v_add_f32_e32 v71, v160, v71
	v_and_b32_e32 v161, 0xffff0000, v85
	v_and_b32_e32 v160, 0xffff0000, v81
	v_pk_mul_f32 v[80:81], v[106:107], v[160:161]
	v_and_b32_e32 v85, 0xffff0000, v101
	v_add_f32_e32 v81, v81, v119
	v_add_f32_e32 v92, v80, v81
	v_pk_mul_f32 v[80:81], v[110:111], v[84:85]
	v_lshlrev_b32_e32 v131, 16, v102
	v_add_f32_e32 v81, v81, v92
	v_add_f32_e32 v137, v80, v81
	v_lshlrev_b32_e32 v81, 16, v86
	v_lshlrev_b32_e32 v80, 16, v82
	v_mov_b32_e32 v92, v120
	v_pk_mul_f32 v[100:101], v[92:93], v[80:81]
	v_lshlrev_b32_e32 v130, 16, v94
	v_add_f32_e32 v81, v101, v112
	v_add_f32_e32 v81, v100, v81
	v_mov_b32_e32 v100, v124
	v_mov_b32_e32 v101, v96
	v_pk_mul_f32 v[134:135], v[100:101], v[130:131]
	v_mov_b32_e32 v96, v125
	v_add_f32_e32 v81, v135, v81
	v_add_f32_e32 v81, v134, v81
	v_and_b32_e32 v135, 0xffff0000, v86
	v_and_b32_e32 v134, 0xffff0000, v82
	v_pk_mul_f32 v[120:121], v[88:89], v[134:135]
	v_and_b32_e32 v86, 0xffff0000, v83
	v_add_f32_e32 v82, v121, v113
	v_add_f32_e32 v82, v120, v82
	v_pk_mul_f32 v[120:121], v[96:97], v[186:187]
	v_and_b32_e32 v102, 0xffff0000, v95
	v_add_f32_e32 v82, v121, v82
	v_add_f32_e32 v94, v120, v82
	v_mov_b32_e32 v120, v122
	v_mov_b32_e32 v121, v90
	v_pk_mul_f32 v[124:125], v[120:121], v[188:189]
	v_mov_b32_e32 v90, v123
	v_add_f32_e32 v82, v125, v114
	v_add_f32_e32 v82, v124, v82
	v_mov_b32_e32 v124, v126
	v_mov_b32_e32 v125, v98
	v_pk_mul_f32 v[180:181], v[124:125], v[190:191]
	v_mov_b32_e32 v98, v127
	v_add_f32_e32 v82, v181, v82
	v_add_f32_e32 v122, v180, v82
	v_pk_mul_f32 v[82:83], v[90:91], v[86:87]
	v_cvt_pk_bf16_f32 v180, v67, v69
	v_cvt_pk_bf16_f32 v181, v71, v137
	v_cvt_pk_bf16_f32 v182, v81, v94
	v_pk_mov_b32 v[80:81], v[130:131], v[80:81] op_sel:[1,0]
	v_add_f32_e32 v83, v83, v115
	v_add_f32_e32 v123, v82, v83
	v_pk_mul_f32 v[82:83], v[98:99], v[102:103]
	v_pk_mul_f32 v[80:81], v[92:93], v[80:81]
	v_add_f32_e32 v83, v83, v123
	v_add_f32_e32 v81, v81, v112
	v_add_f32_e32 v82, v82, v83
	v_add_f32_e32 v137, v80, v81
	v_pk_mov_b32 v[80:81], v[186:187], v[134:135] op_sel:[1,0]
	v_cvt_pk_bf16_f32 v183, v122, v82
	v_pk_mov_b32 v[82:83], v[148:149], v[150:151] op_sel:[1,0]
	v_pk_mul_f32 v[80:81], v[88:89], v[80:81]
	v_mul_lo_u32 v67, v178, s12
	v_pk_mul_f32 v[82:83], v[144:145], v[82:83]
	v_add_f32_e32 v81, v81, v113
	v_add3_u32 v179, s14, v65, v67
	v_add_f32_e32 v65, v83, v116
	v_add_f32_e32 v139, v80, v81
	v_pk_mov_b32 v[80:81], v[190:191], v[188:189] op_sel:[1,0]
	v_add_f32_e32 v65, v82, v65
	v_pk_mov_b32 v[82:83], v[152:153], v[154:155] op_sel:[1,0]
	v_pk_mul_f32 v[80:81], v[120:121], v[80:81]
	v_pk_mul_f32 v[82:83], v[104:105], v[82:83]
	v_add_f32_e32 v81, v81, v114
	v_add_f32_e32 v67, v83, v117
	v_add_f32_e32 v141, v80, v81
	v_pk_mov_b32 v[80:81], v[102:103], v[86:87] op_sel:[1,0]
	v_add_f32_e32 v67, v82, v67
	v_pk_mov_b32 v[82:83], v[156:157], v[158:159] op_sel:[1,0]
	v_pk_mul_f32 v[80:81], v[90:91], v[80:81]
	v_pk_mul_f32 v[82:83], v[128:129], v[82:83]
	v_add_f32_e32 v81, v81, v115
	v_add_f32_e32 v69, v83, v118
	v_add_f32_e32 v143, v80, v81
	v_pk_mul_f32 v[80:81], v[144:145], v[148:149]
	v_add_f32_e32 v69, v82, v69
	v_pk_mov_b32 v[82:83], v[84:85], v[160:161] op_sel:[1,0]
	v_add_f32_e32 v81, v81, v116
	v_pk_mul_f32 v[82:83], v[106:107], v[82:83]
	v_add_f32_e32 v86, v80, v81
	v_lshlrev_b32_e32 v81, 16, v76
	v_lshlrev_b32_e32 v80, 16, v72
	v_add_f32_e32 v71, v83, v119
	v_pk_mov_b32 v[122:123], v[80:81], v[148:149] op_sel:[1,0]
	v_add_f32_e32 v71, v82, v71
	v_pk_mul_f32 v[82:83], v[146:147], v[122:123]
	v_and_b32_e32 v95, 0xffff0000, v76
	v_add_f32_e32 v65, v83, v65
	v_add_f32_e32 v65, v82, v65
	v_pk_mul_f32 v[82:83], v[146:147], v[80:81]
	v_and_b32_e32 v94, 0xffff0000, v72
	v_add_f32_e32 v83, v83, v86
	v_add_f32_e32 v160, v82, v83
	v_pk_mul_f32 v[82:83], v[104:105], v[152:153]
	v_pk_mov_b32 v[126:127], v[94:95], v[152:153] op_sel:[1,0]
	v_add_f32_e32 v83, v83, v117
	v_add_f32_e32 v86, v82, v83
	v_pk_mul_f32 v[82:83], v[108:109], v[126:127]
	ds_write_b128 v179, v[180:183]
	v_add_f32_e32 v67, v83, v67
	v_add_f32_e32 v67, v82, v67
	v_pk_mul_f32 v[82:83], v[108:109], v[94:95]
	v_cvt_pk_bf16_f32 v148, v65, v67
	v_and_b32_e32 v76, 0xffff0000, v73
	v_add_f32_e32 v65, v83, v86
	v_add_f32_e32 v65, v82, v65
	v_pk_mul_f32 v[82:83], v[128:129], v[156:157]
	s_nop 0
	v_add_f32_e32 v67, v83, v118
	v_add_f32_e32 v67, v82, v67
	v_lshlrev_b32_e32 v82, 16, v73
	v_lshlrev_b32_e32 v83, 16, v77
	v_pk_mov_b32 v[134:135], v[82:83], v[156:157] op_sel:[1,0]
	v_and_b32_e32 v77, 0xffff0000, v77
	v_pk_mul_f32 v[86:87], v[132:133], v[134:135]
	v_pk_mov_b32 v[152:153], v[76:77], v[84:85] op_sel:[1,0]
	v_add_f32_e32 v69, v87, v69
	v_add_f32_e32 v69, v86, v69
	v_pk_mul_f32 v[86:87], v[132:133], v[82:83]
	s_nop 0
	v_add_f32_e32 v67, v87, v67
	v_add_f32_e32 v67, v86, v67
	v_pk_mul_f32 v[86:87], v[106:107], v[84:85]
	v_lshlrev_b32_e32 v85, 16, v78
	v_add_f32_e32 v72, v87, v119
	v_add_f32_e32 v86, v86, v72
	v_pk_mul_f32 v[72:73], v[110:111], v[152:153]
	v_lshlrev_b32_e32 v84, 16, v74
	v_add_f32_e32 v71, v73, v71
	v_add_f32_e32 v71, v72, v71
	v_pk_mul_f32 v[72:73], v[110:111], v[76:77]
	v_cvt_pk_bf16_f32 v149, v69, v71
	s_nop 0
	v_add_f32_e32 v69, v73, v86
	v_add_f32_e32 v69, v72, v69
	v_pk_mul_f32 v[72:73], v[92:93], v[130:131]
	v_pk_mov_b32 v[130:131], v[84:85], v[130:131] op_sel:[1,0]
	v_add_f32_e32 v71, v73, v112
	v_add_f32_e32 v71, v72, v71
	v_pk_mul_f32 v[72:73], v[100:101], v[130:131]
	v_pk_mul_f32 v[92:93], v[92:93], v[130:131]
	v_add_f32_e32 v73, v73, v137
	v_add_f32_e32 v137, v72, v73
	v_pk_mul_f32 v[72:73], v[100:101], v[84:85]
	s_nop 0
	v_add_f32_e32 v71, v73, v71
	v_add_f32_e32 v71, v72, v71
	v_pk_mul_f32 v[72:73], v[88:89], v[186:187]
	s_nop 0
	v_add_f32_e32 v73, v73, v113
	v_add_f32_e32 v151, v72, v73
	v_and_b32_e32 v73, 0xffff0000, v78
	v_and_b32_e32 v72, 0xffff0000, v74
	v_pk_mov_b32 v[154:155], v[72:73], v[186:187] op_sel:[1,0]
	s_nop 0
	v_pk_mul_f32 v[86:87], v[96:97], v[154:155]
	v_pk_mul_f32 v[88:89], v[88:89], v[154:155]
	v_add_f32_e32 v74, v87, v139
	v_add_f32_e32 v74, v86, v74
	v_pk_mul_f32 v[86:87], v[96:97], v[72:73]
	v_cvt_pk_bf16_f32 v150, v137, v74
	s_nop 0
	v_add_f32_e32 v74, v87, v151
	v_add_f32_e32 v137, v86, v74
	v_pk_mul_f32 v[86:87], v[120:121], v[190:191]
	s_nop 0
	v_add_f32_e32 v74, v87, v114
	v_add_f32_e32 v74, v86, v74
	v_lshlrev_b32_e32 v86, 16, v75
	v_lshlrev_b32_e32 v87, 16, v79
	v_pk_mov_b32 v[156:157], v[86:87], v[190:191] op_sel:[1,0]
	v_and_b32_e32 v79, 0xffff0000, v79
	v_pk_mul_f32 v[158:159], v[124:125], v[156:157]
	s_nop 0
	v_add_f32_e32 v78, v159, v141
	v_add_f32_e32 v139, v158, v78
	v_pk_mul_f32 v[158:159], v[124:125], v[86:87]
	v_and_b32_e32 v78, 0xffff0000, v75
	v_add_f32_e32 v74, v159, v74
	v_add_f32_e32 v141, v158, v74
	v_pk_mul_f32 v[158:159], v[90:91], v[102:103]
	s_nop 0
	v_add_f32_e32 v74, v159, v115
	v_add_f32_e32 v158, v158, v74
	v_pk_mov_b32 v[74:75], v[78:79], v[102:103] op_sel:[1,0]
	s_nop 0
	v_pk_mul_f32 v[102:103], v[98:99], v[74:75]
	v_pk_mul_f32 v[74:75], v[90:91], v[74:75]
	v_add_f32_e32 v103, v103, v143
	v_add_f32_e32 v102, v102, v103
	v_cvt_pk_bf16_f32 v151, v139, v102
	v_pk_mul_f32 v[102:103], v[98:99], v[78:79]
	ds_write_b128 v179, v[148:151] offset:528
	v_add_f32_e32 v103, v103, v158
	v_add_f32_e32 v102, v102, v103
	v_cvt_pk_bf16_f32 v148, v160, v65
	v_cvt_pk_bf16_f32 v149, v67, v69
	v_cvt_pk_bf16_f32 v150, v71, v137
	v_cvt_pk_bf16_f32 v151, v141, v102
	v_pk_mul_f32 v[102:103], v[144:145], v[122:123]
	v_mov_b32_e32 v69, v80
	v_add_f32_e32 v65, v103, v116
	v_add_f32_e32 v65, v102, v65
	v_pk_mul_f32 v[102:103], v[146:147], v[68:69]
	v_mov_b32_e32 v143, v94
	v_add_f32_e32 v65, v103, v65
	v_add_f32_e32 v69, v102, v65
	v_pk_mul_f32 v[102:103], v[104:105], v[126:127]
	v_mov_b32_e32 v71, v82
	v_add_f32_e32 v65, v103, v117
	v_add_f32_e32 v65, v102, v65
	v_pk_mul_f32 v[102:103], v[108:109], v[142:143]
	v_mov_b32_e32 v141, v76
	v_add_f32_e32 v65, v103, v65
	v_add_f32_e32 v104, v102, v65
	v_pk_mul_f32 v[102:103], v[128:129], v[134:135]
	v_mov_b32_e32 v139, v72
	v_add_f32_e32 v65, v103, v118
	v_add_f32_e32 v65, v102, v65
	v_pk_mul_f32 v[102:103], v[132:133], v[70:71]
	v_add_f32_e32 v75, v75, v115
	v_add_f32_e32 v65, v103, v65
	v_add_f32_e32 v71, v102, v65
	v_pk_mul_f32 v[102:103], v[106:107], v[152:153]
	v_mov_b32_e32 v137, v78
	v_add_f32_e32 v65, v103, v119
	v_add_f32_e32 v65, v102, v65
	v_pk_mul_f32 v[102:103], v[110:111], v[140:141]
	ds_write_b128 v179, v[148:151] offset:1056
	v_add_f32_e32 v65, v103, v65
	v_add_f32_e32 v102, v102, v65
	v_add_f32_e32 v65, v93, v112
	v_add_f32_e32 v67, v92, v65
	v_mov_b32_e32 v65, v84
	v_pk_mul_f32 v[92:93], v[100:101], v[64:65]
	s_nop 0
	v_add_f32_e32 v65, v93, v67
	v_add_f32_e32 v67, v89, v113
	v_add_f32_e32 v67, v88, v67
	v_pk_mul_f32 v[88:89], v[96:97], v[138:139]
	v_add_f32_e32 v65, v92, v65
	v_add_f32_e32 v67, v89, v67
	v_add_f32_e32 v92, v88, v67
	v_pk_mul_f32 v[88:89], v[120:121], v[156:157]
	s_nop 0
	v_add_f32_e32 v67, v89, v114
	v_add_f32_e32 v93, v88, v67
	v_mov_b32_e32 v67, v86
	v_pk_mul_f32 v[88:89], v[124:125], v[66:67]
	s_nop 0
	v_add_f32_e32 v67, v89, v93
	v_add_f32_e32 v67, v88, v67
	v_add_f32_e32 v88, v74, v75
	v_pk_mul_f32 v[74:75], v[98:99], v[136:137]
	s_nop 0
	v_add_f32_e32 v75, v75, v88
	v_add_f32_e32 v74, v74, v75
	v_cvt_pk_bf16_f32 v88, v69, v104
	v_cvt_pk_bf16_f32 v89, v71, v102
	v_cvt_pk_bf16_f32 v90, v65, v92
	v_cvt_pk_bf16_f32 v91, v67, v74
	ds_write_b128 v179, v[88:91] offset:1584
	s_and_saveexec_b64 s[12:13], s[16:17]
	s_cbranch_execz .LBB0_685
	s_load_dwordx2 s[16:17], s[80:81], 0xf8
	s_add_i32 s15, s54, s3
	v_mov_b32_e32 v90, v83
	v_mov_b32_e32 v83, v76
	v_mov_b32_e32 v88, v81
	s_waitcnt lgkmcnt(0)
	v_lshl_add_u64 v[74:75], s[16:17], 0, v[184:185]
	s_mov_b64 s[16:17], 0x4410000
	v_lshl_add_u64 v[74:75], v[74:75], 0, s[16:17]
	v_mad_i64_i32 v[74:75], s[16:17], s15, v222, v[74:75]
	v_add_co_u32_e32 v76, vcc, 0x1000, v74
	v_mov_b32_e32 v89, v95
	v_mov_b32_e32 v91, v77
	v_addc_co_u32_e32 v77, vcc, 0, v75, vcc
	global_store_dwordx4 v[74:75], v[88:91], off
	v_mov_b32_e32 v81, v94
	v_mov_b32_e32 v69, v142
	v_mov_b32_e32 v88, v85
	v_mov_b32_e32 v85, v72
	v_add_co_u32_e32 v72, vcc, 0x2000, v74
	v_mov_b32_e32 v89, v73
	v_mov_b32_e32 v90, v87
	v_mov_b32_e32 v91, v79
	v_mov_b32_e32 v87, v78
	v_mov_b32_e32 v71, v140
	v_addc_co_u32_e32 v73, vcc, 0, v75, vcc
	v_mov_b32_e32 v65, v138
	v_mov_b32_e32 v67, v136
	global_store_dwordx4 v[74:75], v[88:91], off offset:16
	global_store_dwordx4 v[76:77], v[80:83], off
	global_store_dwordx4 v[76:77], v[84:87], off offset:16
	global_store_dwordx4 v[72:73], v[68:71], off
	global_store_dwordx4 v[72:73], v[64:67], off offset:16
